# P1 K-loop LDS-DMA loads use SGPR base + 32-bit lane offset instead of 64-bit VGPR addresses
# baseline (speedup 1.0000x reference)
; #define PG8_STAGE(bufoff, gbase, voff) do { _Pragma("unroll") for (int _i = 0; _i < 2; ++_i) \
;         __builtin_amdgcn_global_load_lds((const unsigned*)((const char*)(gbase) + (voff)[_i]), (LAS unsigned*)(lds + (bufoff) + ldsw + _i * 8192), 16, 0, 0); } while (0)
; #define PG8_LDA(dst, b, h) do { _Pragma("unroll") for (int m = 0; m < 4; ++m) _Pragma("unroll") for (int k = 0; k < 2; ++k) dst[m][k] = *(const LAS bf16x8*)(lds + PG8_SA(b, h) + aoff + m * 2048 + k * 1024); } while (0)
; #define PG8_LDB(dst, b, h) do { _Pragma("unroll") for (int n = 0; n < 2; ++n) _Pragma("unroll") for (int k = 0; k < 2; ++k) dst[n][k] = *(const LAS bf16x8*)(lds + PG8_SB(b, h) + boff + n * 2048 + k * 1024); } while (0)
; #define PG8_MMA(ai, bj, At, Bt) do { __builtin_amdgcn_s_setprio(1); _Pragma("unroll") for (int m = 0; m < 4; ++m) _Pragma("unroll") for (int n = 0; n < 2; ++n) _Pragma("unroll") for (int k = 0; k < 2; ++k) \
;         acc[ai][bj][m][n] = __builtin_amdgcn_mfma_f32_16x16x32_bf16(Bt[n][k], At[m][k], acc[ai][bj][m][n], 0, 0, 0); __builtin_amdgcn_s_setprio(0); } while (0)
; #define PG8_WAIT_V(n) asm volatile("s_waitcnt vmcnt(" #n ")" ::: "memory")
; #define PG8_WAIT_L(n) asm volatile("s_waitcnt lgkmcnt(" #n ")" ::: "memory")
; #define PG8_BAR __builtin_amdgcn_s_barrier()
; #define PG8_SCHED __builtin_amdgcn_sched_barrier(0)
; template <class Epi, bool ALIGN_EPI>
; __device__ __forceinline__ void gemm_phase(LAS unsigned char* lds, const Gemm g, const StaticOrder& S, const Epi& E) {
;     ...
;             PG8_LDB(B0, 0, 0); PG8_LDB(B1, 0, 1); PG8_SCHED; PG8_LDA(At, 0, 0); PG8_STAGE(PG8_SA(1, 1), a1 + hsA, voffA);
;             PG8_WAIT_V(8); PG8_WAIT_L(0); PG8_BAR; PG8_MMA(0, 0, At, B0); PG8_MMA(0, 1, At, B1); PG8_BAR; PG8_SCHED;
;             PG8_LDA(At, 0, 1); PG8_STAGE(PG8_SB(0, 0), b2, voffB); PG8_STAGE(PG8_SB(0, 1), b2 + hsB, voffB); PG8_STAGE(PG8_SA(0, 0), a2, voffA);
;             PG8_WAIT_V(8); PG8_WAIT_L(0); PG8_BAR; PG8_MMA(1, 0, At, B0); PG8_MMA(1, 1, At, B1); PG8_BAR; PG8_SCHED;
.LBB0_156:
	ds_read_b128 v[156:159], v151
	ds_read_b128 v[160:163], v151 offset:1024
	ds_read_b128 v[164:167], v151 offset:2048
	ds_read_b128 v[168:171], v151 offset:3072
	ds_read_b128 v[172:175], v152
	ds_read_b128 v[176:179], v152 offset:1024
	ds_read_b128 v[180:183], v152 offset:2048
	ds_read_b128 v[184:187], v152 offset:3072
	s_add_u32 s28, s26, 0xfffc0080
	s_addc_u32 s29, s27, -1
	s_cmp_eq_u32 s54, 12
	s_cselect_b32 s31, s17, s29
	s_cselect_b32 s30, s50, s28
	s_cselect_b32 s29, s19, s53
	s_cselect_b32 s28, s51, s52
	s_add_i32 m0, s25, 0xc000
	ds_read_b128 v[188:191], v153
	ds_read_b128 v[192:195], v153 offset:1024
	ds_read_b128 v[196:199], v153 offset:2048
	ds_read_b128 v[200:203], v153 offset:3072
	ds_read_b128 v[204:207], v153 offset:4096
	ds_read_b128 v[208:211], v153 offset:5120
	ds_read_b128 v[212:215], v153 offset:6144
	ds_read_b128 v[216:219], v153 offset:7168
	global_load_lds_dwordx4 v140, s[26:27]
	s_add_i32 m0, s25, 0xe000
	s_nop 0
	global_load_lds_dwordx4 v142, s[26:27]
	s_waitcnt vmcnt(8)
	s_waitcnt lgkmcnt(0)
	s_barrier
	s_setprio 1
	s_waitcnt lgkmcnt(0)
	v_mfma_f32_16x16x32_bf16 v[118:121], v[156:159], v[188:191], v[118:121]
	v_mfma_f32_16x16x32_bf16 v[114:117], v[164:167], v[188:191], v[114:117]
	v_mfma_f32_16x16x32_bf16 v[106:109], v[156:159], v[196:199], v[106:109]
	v_mfma_f32_16x16x32_bf16 v[102:105], v[164:167], v[196:199], v[102:105]
	v_mfma_f32_16x16x32_bf16 v[94:97], v[156:159], v[204:207], v[94:97]
	v_mfma_f32_16x16x32_bf16 v[90:93], v[164:167], v[204:207], v[90:93]
	v_mfma_f32_16x16x32_bf16 v[78:81], v[156:159], v[212:215], v[78:81]
	v_mfma_f32_16x16x32_bf16 v[74:77], v[164:167], v[212:215], v[74:77]
	v_mfma_f32_16x16x32_bf16 v[118:121], v[160:163], v[192:195], v[118:121]
	v_mfma_f32_16x16x32_bf16 v[114:117], v[168:171], v[192:195], v[114:117]
	v_mfma_f32_16x16x32_bf16 v[106:109], v[160:163], v[200:203], v[106:109]
	v_mfma_f32_16x16x32_bf16 v[102:105], v[168:171], v[200:203], v[102:105]
	v_mfma_f32_16x16x32_bf16 v[94:97], v[160:163], v[208:211], v[94:97]
	v_mfma_f32_16x16x32_bf16 v[90:93], v[168:171], v[208:211], v[90:93]
	v_mfma_f32_16x16x32_bf16 v[78:81], v[160:163], v[216:219], v[78:81]
	v_mfma_f32_16x16x32_bf16 v[74:77], v[168:171], v[216:219], v[74:77]
	s_setprio 0
	s_setprio 1
	v_mfma_f32_16x16x32_bf16 v[126:129], v[172:175], v[188:191], v[126:129]
	v_mfma_f32_16x16x32_bf16 v[122:125], v[180:183], v[188:191], v[122:125]
	v_mfma_f32_16x16x32_bf16 v[110:113], v[172:175], v[196:199], v[110:113]
	v_mfma_f32_16x16x32_bf16 v[98:101], v[180:183], v[196:199], v[98:101]
	v_mfma_f32_16x16x32_bf16 v[86:89], v[172:175], v[204:207], v[86:89]
	v_mfma_f32_16x16x32_bf16 v[82:85], v[180:183], v[204:207], v[82:85]
	v_mfma_f32_16x16x32_bf16 v[70:73], v[172:175], v[212:215], v[70:73]
	v_mfma_f32_16x16x32_bf16 v[66:69], v[180:183], v[212:215], v[66:69]
	v_mfma_f32_16x16x32_bf16 v[126:129], v[176:179], v[192:195], v[126:129]
	v_mfma_f32_16x16x32_bf16 v[122:125], v[184:187], v[192:195], v[122:125]
	v_mfma_f32_16x16x32_bf16 v[110:113], v[176:179], v[200:203], v[110:113]
	v_mfma_f32_16x16x32_bf16 v[98:101], v[184:187], v[200:203], v[98:101]
	v_mfma_f32_16x16x32_bf16 v[86:89], v[176:179], v[208:211], v[86:89]
	v_mfma_f32_16x16x32_bf16 v[82:85], v[184:187], v[208:211], v[82:85]
	v_mfma_f32_16x16x32_bf16 v[70:73], v[176:179], v[216:219], v[70:73]
	v_mfma_f32_16x16x32_bf16 v[66:69], v[184:187], v[216:219], v[66:69]
	s_setprio 0
	s_barrier
	s_add_i32 s55, s46, s33
	s_mov_b32 m0, s55
	ds_read_b128 v[188:191], v153 offset:16384
	ds_read_b128 v[192:195], v153 offset:17408
	ds_read_b128 v[196:199], v153 offset:18432
	ds_read_b128 v[200:203], v153 offset:19456
	ds_read_b128 v[204:207], v153 offset:20480
	ds_read_b128 v[208:211], v153 offset:21504
	ds_read_b128 v[212:215], v153 offset:22528
	ds_read_b128 v[216:219], v153 offset:23552
	global_load_lds_dwordx4 v134, s[28:29]
	s_add_i32 m0, s55, 0x2000
	s_add_u32 s56, s28, 0x40000
	s_addc_u32 s57, s29, 0
	s_add_i32 s55, s47, s33
	global_load_lds_dwordx4 v130, s[28:29]
	s_mov_b32 m0, s55
	s_nop 0
	global_load_lds_dwordx4 v134, s[56:57]
	s_add_i32 m0, s55, 0x2000
	s_nop 0
	global_load_lds_dwordx4 v130, s[56:57]
	s_mov_b32 m0, s25
	s_nop 0
	global_load_lds_dwordx4 v136, s[30:31]
	s_mov_b32 m0, s36
	s_nop 0
	global_load_lds_dwordx4 v132, s[30:31]
	s_waitcnt vmcnt(8)
	s_waitcnt lgkmcnt(0)
	s_barrier
	s_setprio 1
	s_waitcnt lgkmcnt(0)
	v_mfma_f32_16x16x32_bf16 v[62:65], v[156:159], v[188:191], v[62:65]
	v_mfma_f32_16x16x32_bf16 v[58:61], v[164:167], v[188:191], v[58:61]
	v_mfma_f32_16x16x32_bf16 v[46:49], v[156:159], v[196:199], v[46:49]
	v_mfma_f32_16x16x32_bf16 v[42:45], v[164:167], v[196:199], v[42:45]
	v_mfma_f32_16x16x32_bf16 v[30:33], v[156:159], v[204:207], v[30:33]
	v_mfma_f32_16x16x32_bf16 v[26:29], v[164:167], v[204:207], v[26:29]
	v_mfma_f32_16x16x32_bf16 v[14:17], v[156:159], v[212:215], v[14:17]
	v_mfma_f32_16x16x32_bf16 v[10:13], v[164:167], v[212:215], v[10:13]
	v_mfma_f32_16x16x32_bf16 v[62:65], v[160:163], v[192:195], v[62:65]
	v_mfma_f32_16x16x32_bf16 v[58:61], v[168:171], v[192:195], v[58:61]
	v_mfma_f32_16x16x32_bf16 v[46:49], v[160:163], v[200:203], v[46:49]
	v_mfma_f32_16x16x32_bf16 v[42:45], v[168:171], v[200:203], v[42:45]
	v_mfma_f32_16x16x32_bf16 v[30:33], v[160:163], v[208:211], v[30:33]
	v_mfma_f32_16x16x32_bf16 v[26:29], v[168:171], v[208:211], v[26:29]
	v_mfma_f32_16x16x32_bf16 v[14:17], v[160:163], v[216:219], v[14:17]
	v_mfma_f32_16x16x32_bf16 v[10:13], v[168:171], v[216:219], v[10:13]
	s_setprio 0
	s_setprio 1
	v_mfma_f32_16x16x32_bf16 v[54:57], v[172:175], v[188:191], v[54:57]
	v_mfma_f32_16x16x32_bf16 v[50:53], v[180:183], v[188:191], v[50:53]
	v_mfma_f32_16x16x32_bf16 v[38:41], v[172:175], v[196:199], v[38:41]
	v_mfma_f32_16x16x32_bf16 v[34:37], v[180:183], v[196:199], v[34:37]
	v_mfma_f32_16x16x32_bf16 v[22:25], v[172:175], v[204:207], v[22:25]
	v_mfma_f32_16x16x32_bf16 v[18:21], v[180:183], v[204:207], v[18:21]
	v_mfma_f32_16x16x32_bf16 v[6:9], v[172:175], v[212:215], v[6:9]
	v_mfma_f32_16x16x32_bf16 v[2:5], v[180:183], v[212:215], v[2:5]
	v_mfma_f32_16x16x32_bf16 v[54:57], v[176:179], v[192:195], v[54:57]
	v_mfma_f32_16x16x32_bf16 v[50:53], v[184:187], v[192:195], v[50:53]
	v_mfma_f32_16x16x32_bf16 v[38:41], v[176:179], v[200:203], v[38:41]
	v_mfma_f32_16x16x32_bf16 v[34:37], v[184:187], v[200:203], v[34:37]
	v_mfma_f32_16x16x32_bf16 v[22:25], v[176:179], v[208:211], v[22:25]
	v_mfma_f32_16x16x32_bf16 v[18:21], v[184:187], v[208:211], v[18:21]
	v_mfma_f32_16x16x32_bf16 v[6:9], v[176:179], v[216:219], v[6:9]
	v_mfma_f32_16x16x32_bf16 v[2:5], v[184:187], v[216:219], v[2:5]
	s_setprio 0
	s_barrier
; #define PG8_STAGE(bufoff, gbase, voff) do { _Pragma("unroll") for (int _i = 0; _i < 2; ++_i) \
;         __builtin_amdgcn_global_load_lds((const unsigned*)((const char*)(gbase) + (voff)[_i]), (LAS unsigned*)(lds + (bufoff) + ldsw + _i * 8192), 16, 0, 0); } while (0)
; #define PG8_LDA(dst, b, h) do { _Pragma("unroll") for (int m = 0; m < 4; ++m) _Pragma("unroll") for (int k = 0; k < 2; ++k) dst[m][k] = *(const LAS bf16x8*)(lds + PG8_SA(b, h) + aoff + m * 2048 + k * 1024); } while (0)
; #define PG8_LDB(dst, b, h) do { _Pragma("unroll") for (int n = 0; n < 2; ++n) _Pragma("unroll") for (int k = 0; k < 2; ++k) dst[n][k] = *(const LAS bf16x8*)(lds + PG8_SB(b, h) + boff + n * 2048 + k * 1024); } while (0)
; #define PG8_MMA(ai, bj, At, Bt) do { __builtin_amdgcn_s_setprio(1); _Pragma("unroll") for (int m = 0; m < 4; ++m) _Pragma("unroll") for (int n = 0; n < 2; ++n) _Pragma("unroll") for (int k = 0; k < 2; ++k) \
;         acc[ai][bj][m][n] = __builtin_amdgcn_mfma_f32_16x16x32_bf16(Bt[n][k], At[m][k], acc[ai][bj][m][n], 0, 0, 0); __builtin_amdgcn_s_setprio(0); } while (0)
; #define PG8_WAIT_V(n) asm volatile("s_waitcnt vmcnt(" #n ")" ::: "memory")
; #define PG8_WAIT_L(n) asm volatile("s_waitcnt lgkmcnt(" #n ")" ::: "memory")
; #define PG8_BAR __builtin_amdgcn_s_barrier()
; #define PG8_SCHED __builtin_amdgcn_sched_barrier(0)
; template <class Epi, bool ALIGN_EPI>
; __device__ __forceinline__ void gemm_phase(LAS unsigned char* lds, const Gemm g, const StaticOrder& S, const Epi& E) {
;     ...
;             PG8_LDB(B0, 1, 0); PG8_LDB(B1, 1, 1); PG8_SCHED; PG8_LDA(At, 1, 0); PG8_STAGE(PG8_SA(0, 1), a2 + hsA, voffA);
;             PG8_WAIT_V(8); PG8_WAIT_L(0); PG8_BAR; PG8_MMA(0, 0, At, B0); PG8_MMA(0, 1, At, B1); PG8_BAR; PG8_SCHED;
;             PG8_LDA(At, 1, 1); PG8_STAGE(PG8_SB(1, 0), b3, voffB); PG8_STAGE(PG8_SB(1, 1), b3 + hsB, voffB); PG8_STAGE(PG8_SA(1, 0), a3, voffA);
;             PG8_WAIT_V(8); PG8_WAIT_L(0); PG8_BAR; PG8_MMA(1, 0, At, B0); PG8_MMA(1, 1, At, B1); PG8_BAR; PG8_SCHED;
;         }
	s_add_i32 s55, 0, 0x18000
	v_add_u32_e32 v138, s55, v150
	s_add_i32 s56, 0, 0x1c000
	ds_read_b128 v[156:159], v138
	ds_read_b128 v[160:163], v138 offset:1024
	ds_read_b128 v[164:167], v138 offset:2048
	ds_read_b128 v[168:171], v138 offset:3072
	v_add_u32_e32 v138, s56, v150
	ds_read_b128 v[172:175], v138
	ds_read_b128 v[176:179], v138 offset:1024
	ds_read_b128 v[180:183], v138 offset:2048
	ds_read_b128 v[184:187], v138 offset:3072
	s_add_u32 s30, s30, 0x40000
	s_addc_u32 s31, s31, 0
	s_mov_b32 m0, s37
	ds_read_b128 v[188:191], v153 offset:32768
	ds_read_b128 v[192:195], v153 offset:33792
	ds_read_b128 v[196:199], v153 offset:34816
	ds_read_b128 v[200:203], v153 offset:35840
	ds_read_b128 v[204:207], v153 offset:36864
	ds_read_b128 v[208:211], v153 offset:37888
	ds_read_b128 v[212:215], v153 offset:38912
	ds_read_b128 v[216:219], v153 offset:39936
	global_load_lds_dwordx4 v136, s[30:31]
	s_mov_b32 m0, s38
	s_nop 0
	global_load_lds_dwordx4 v132, s[30:31]
	s_waitcnt vmcnt(8)
	s_waitcnt lgkmcnt(0)
	s_barrier
	s_setprio 1
	s_waitcnt lgkmcnt(0)
	v_mfma_f32_16x16x32_bf16 v[118:121], v[156:159], v[188:191], v[118:121]
	v_mfma_f32_16x16x32_bf16 v[114:117], v[164:167], v[188:191], v[114:117]
	v_mfma_f32_16x16x32_bf16 v[106:109], v[156:159], v[196:199], v[106:109]
	v_mfma_f32_16x16x32_bf16 v[102:105], v[164:167], v[196:199], v[102:105]
	v_mfma_f32_16x16x32_bf16 v[94:97], v[156:159], v[204:207], v[94:97]
	v_mfma_f32_16x16x32_bf16 v[90:93], v[164:167], v[204:207], v[90:93]
	v_mfma_f32_16x16x32_bf16 v[78:81], v[156:159], v[212:215], v[78:81]
	v_mfma_f32_16x16x32_bf16 v[74:77], v[164:167], v[212:215], v[74:77]
	v_mfma_f32_16x16x32_bf16 v[118:121], v[160:163], v[192:195], v[118:121]
	v_mfma_f32_16x16x32_bf16 v[114:117], v[168:171], v[192:195], v[114:117]
	v_mfma_f32_16x16x32_bf16 v[106:109], v[160:163], v[200:203], v[106:109]
	v_mfma_f32_16x16x32_bf16 v[102:105], v[168:171], v[200:203], v[102:105]
	v_mfma_f32_16x16x32_bf16 v[94:97], v[160:163], v[208:211], v[94:97]
	v_mfma_f32_16x16x32_bf16 v[90:93], v[168:171], v[208:211], v[90:93]
	v_mfma_f32_16x16x32_bf16 v[78:81], v[160:163], v[216:219], v[78:81]
	v_mfma_f32_16x16x32_bf16 v[74:77], v[168:171], v[216:219], v[74:77]
	s_setprio 0
	s_setprio 1
	v_mfma_f32_16x16x32_bf16 v[126:129], v[172:175], v[188:191], v[126:129]
	v_mfma_f32_16x16x32_bf16 v[122:125], v[180:183], v[188:191], v[122:125]
	v_mfma_f32_16x16x32_bf16 v[110:113], v[172:175], v[196:199], v[110:113]
	v_mfma_f32_16x16x32_bf16 v[98:101], v[180:183], v[196:199], v[98:101]
	v_mfma_f32_16x16x32_bf16 v[86:89], v[172:175], v[204:207], v[86:89]
	v_mfma_f32_16x16x32_bf16 v[82:85], v[180:183], v[204:207], v[82:85]
	v_mfma_f32_16x16x32_bf16 v[70:73], v[172:175], v[212:215], v[70:73]
	v_mfma_f32_16x16x32_bf16 v[66:69], v[180:183], v[212:215], v[66:69]
	v_mfma_f32_16x16x32_bf16 v[126:129], v[176:179], v[192:195], v[126:129]
	v_mfma_f32_16x16x32_bf16 v[122:125], v[184:187], v[192:195], v[122:125]
	v_mfma_f32_16x16x32_bf16 v[110:113], v[176:179], v[200:203], v[110:113]
	v_mfma_f32_16x16x32_bf16 v[98:101], v[184:187], v[200:203], v[98:101]
	v_mfma_f32_16x16x32_bf16 v[86:89], v[176:179], v[208:211], v[86:89]
	v_mfma_f32_16x16x32_bf16 v[82:85], v[184:187], v[208:211], v[82:85]
	v_mfma_f32_16x16x32_bf16 v[70:73], v[176:179], v[216:219], v[70:73]
	v_mfma_f32_16x16x32_bf16 v[66:69], v[184:187], v[216:219], v[66:69]
	s_setprio 0
	s_barrier
	s_add_u32 s98, s28, 0x80
	s_addc_u32 s99, s29, 0
	s_add_u32 s100, s30, 0xfffc0080
	s_addc_u32 s101, s31, -1
	s_add_i32 s30, s55, s33
	s_mov_b32 m0, s30
	ds_read_b128 v[188:191], v153 offset:49152
	ds_read_b128 v[192:195], v153 offset:50176
	ds_read_b128 v[196:199], v153 offset:51200
	ds_read_b128 v[200:203], v153 offset:52224
	ds_read_b128 v[204:207], v153 offset:53248
	ds_read_b128 v[208:211], v153 offset:54272
	ds_read_b128 v[212:215], v153 offset:55296
	ds_read_b128 v[216:219], v153 offset:56320
	global_load_lds_dwordx4 v134, s[98:99]
	s_add_i32 m0, s30, 0x2000
	s_add_u32 s28, s28, 0x40080
	s_addc_u32 s29, s29, 0
	s_add_i32 s30, s56, s33
	global_load_lds_dwordx4 v130, s[98:99]
	s_mov_b32 m0, s30
	s_nop 0
	global_load_lds_dwordx4 v134, s[28:29]
	s_add_i32 m0, s30, 0x2000
	s_nop 0
	global_load_lds_dwordx4 v130, s[28:29]
	s_mov_b32 m0, s42
	s_nop 0
	global_load_lds_dwordx4 v136, s[100:101]
	s_mov_b32 m0, s43
	s_nop 0
	global_load_lds_dwordx4 v132, s[100:101]
	s_waitcnt vmcnt(8)
	s_waitcnt lgkmcnt(0)
	s_barrier
	s_setprio 1
	s_waitcnt lgkmcnt(0)
	v_mfma_f32_16x16x32_bf16 v[62:65], v[156:159], v[188:191], v[62:65]
	v_mfma_f32_16x16x32_bf16 v[58:61], v[164:167], v[188:191], v[58:61]
	v_mfma_f32_16x16x32_bf16 v[46:49], v[156:159], v[196:199], v[46:49]
	v_mfma_f32_16x16x32_bf16 v[42:45], v[164:167], v[196:199], v[42:45]
	v_mfma_f32_16x16x32_bf16 v[30:33], v[156:159], v[204:207], v[30:33]
	v_mfma_f32_16x16x32_bf16 v[26:29], v[164:167], v[204:207], v[26:29]
	v_mfma_f32_16x16x32_bf16 v[14:17], v[156:159], v[212:215], v[14:17]
	v_mfma_f32_16x16x32_bf16 v[10:13], v[164:167], v[212:215], v[10:13]
	v_mfma_f32_16x16x32_bf16 v[62:65], v[160:163], v[192:195], v[62:65]
	v_mfma_f32_16x16x32_bf16 v[58:61], v[168:171], v[192:195], v[58:61]
	v_mfma_f32_16x16x32_bf16 v[46:49], v[160:163], v[200:203], v[46:49]
	v_mfma_f32_16x16x32_bf16 v[42:45], v[168:171], v[200:203], v[42:45]
	v_mfma_f32_16x16x32_bf16 v[30:33], v[160:163], v[208:211], v[30:33]
	v_mfma_f32_16x16x32_bf16 v[26:29], v[168:171], v[208:211], v[26:29]
	v_mfma_f32_16x16x32_bf16 v[14:17], v[160:163], v[216:219], v[14:17]
	v_mfma_f32_16x16x32_bf16 v[10:13], v[168:171], v[216:219], v[10:13]
	s_setprio 0
	s_setprio 1
	v_mfma_f32_16x16x32_bf16 v[54:57], v[172:175], v[188:191], v[54:57]
	v_mfma_f32_16x16x32_bf16 v[50:53], v[180:183], v[188:191], v[50:53]
	v_mfma_f32_16x16x32_bf16 v[38:41], v[172:175], v[196:199], v[38:41]
	v_mfma_f32_16x16x32_bf16 v[34:37], v[180:183], v[196:199], v[34:37]
	v_mfma_f32_16x16x32_bf16 v[22:25], v[172:175], v[204:207], v[22:25]
	v_mfma_f32_16x16x32_bf16 v[18:21], v[180:183], v[204:207], v[18:21]
	v_mfma_f32_16x16x32_bf16 v[6:9], v[172:175], v[212:215], v[6:9]
	v_mfma_f32_16x16x32_bf16 v[2:5], v[180:183], v[212:215], v[2:5]
	v_mfma_f32_16x16x32_bf16 v[54:57], v[176:179], v[192:195], v[54:57]
	v_mfma_f32_16x16x32_bf16 v[50:53], v[184:187], v[192:195], v[50:53]
	v_mfma_f32_16x16x32_bf16 v[38:41], v[176:179], v[200:203], v[38:41]
	v_mfma_f32_16x16x32_bf16 v[34:37], v[184:187], v[200:203], v[34:37]
	v_mfma_f32_16x16x32_bf16 v[22:25], v[176:179], v[208:211], v[22:25]
	v_mfma_f32_16x16x32_bf16 v[18:21], v[184:187], v[208:211], v[18:21]
	v_mfma_f32_16x16x32_bf16 v[6:9], v[176:179], v[216:219], v[6:9]
	v_mfma_f32_16x16x32_bf16 v[2:5], v[184:187], v[216:219], v[2:5]
	s_setprio 0
	s_barrier
	s_add_i32 s54, s54, 2
	s_add_u32 s26, s26, 0x100
	s_addc_u32 s27, s27, 0
	s_add_u32 s52, s52, 0x100
	s_addc_u32 s53, s53, 0
	s_cmp_gt_u32 s54, 13
	s_cbranch_scc0 .LBB0_156
	s_and_b64 vcc, exec, s[14:15]
	s_cbranch_vccz .LBB0_159
	s_barrier

; __global__ void __launch_bounds__(NWAVES * 64, 2) mega_fwd(Args args) {
	.amdhsa_kernel _Z8mega_fwd4Args
		.amdhsa_group_segment_fixed_size 0
		.amdhsa_private_segment_fixed_size 0
		.amdhsa_kernarg_size 520
		.amdhsa_user_sgpr_count 2
		.amdhsa_user_sgpr_dispatch_ptr 0
		.amdhsa_user_sgpr_queue_ptr 0
		.amdhsa_user_sgpr_kernarg_segment_ptr 1
		.amdhsa_user_sgpr_dispatch_id 0
		.amdhsa_user_sgpr_kernarg_preload_length 0
		.amdhsa_user_sgpr_kernarg_preload_offset 0
		.amdhsa_user_sgpr_private_segment_size 0
		.amdhsa_uses_dynamic_stack 0
		.amdhsa_enable_private_segment 0
		.amdhsa_system_sgpr_workgroup_id_x 1
		.amdhsa_system_sgpr_workgroup_id_y 0
		.amdhsa_system_sgpr_workgroup_id_z 0
		.amdhsa_system_sgpr_workgroup_info 0
		.amdhsa_system_vgpr_workitem_id 0
		.amdhsa_next_free_vgpr 255
		.amdhsa_next_free_sgpr 102
		.amdhsa_accum_offset 256
		.amdhsa_reserve_vcc 1
		.amdhsa_float_round_mode_32 0
		.amdhsa_float_round_mode_16_64 0
		.amdhsa_float_denorm_mode_32 3
		.amdhsa_float_denorm_mode_16_64 3
		.amdhsa_dx10_clamp 1
		.amdhsa_ieee_mode 1
		.amdhsa_fp16_overflow 0
		.amdhsa_tg_split 0
		.amdhsa_exception_fp_ieee_invalid_op 0
		.amdhsa_exception_fp_denorm_src 0
		.amdhsa_exception_fp_ieee_div_zero 0
		.amdhsa_exception_fp_ieee_overflow 0
		.amdhsa_exception_fp_ieee_underflow 0
		.amdhsa_exception_fp_ieee_inexact 0
		.amdhsa_exception_int_div_zero 0
	.end_amdhsa_kernel

; __global__ void __launch_bounds__(NWAVES * 64, 2) mega_fwd(Args args) {
amdhsa.kernels:
  - .agpr_count:     0
    .args:
      - .offset:         0
        .size:           264
        .value_kind:     by_value
      - .offset:         264
        .size:           4
        .value_kind:     hidden_block_count_x
      - .offset:         268
        .size:           4
        .value_kind:     hidden_block_count_y
      - .offset:         272
        .size:           4
        .value_kind:     hidden_block_count_z
      - .offset:         276
        .size:           2
        .value_kind:     hidden_group_size_x
      - .offset:         278
        .size:           2
        .value_kind:     hidden_group_size_y
      - .offset:         280
        .size:           2
        .value_kind:     hidden_group_size_z
      - .offset:         282
        .size:           2
        .value_kind:     hidden_remainder_x
      - .offset:         284
        .size:           2
        .value_kind:     hidden_remainder_y
      - .offset:         286
        .size:           2
        .value_kind:     hidden_remainder_z
      - .offset:         304
        .size:           8
        .value_kind:     hidden_global_offset_x
      - .offset:         312
        .size:           8
        .value_kind:     hidden_global_offset_y
      - .offset:         320
        .size:           8
        .value_kind:     hidden_global_offset_z
      - .offset:         328
        .size:           2
        .value_kind:     hidden_grid_dims
      - .offset:         352
        .size:           8
        .value_kind:     hidden_multigrid_sync_arg
      - .offset:         384
        .size:           4
        .value_kind:     hidden_dynamic_lds_size
    .group_segment_fixed_size: 0
    .kernarg_segment_align: 8
    .kernarg_segment_size: 520
    .language:       OpenCL C
    .language_version:
      - 2
      - 0
    .max_flat_workgroup_size: 512
    .name:           _Z8mega_fwd4Args
    .private_segment_fixed_size: 0
    .sgpr_count:     108
    .sgpr_spill_count: 291
    .symbol:         _Z8mega_fwd4Args.kd
    .uniform_work_group_size: 1
    .uses_dynamic_stack: false
    .vgpr_count:     255
    .vgpr_spill_count: 0
    .wavefront_size: 64
